# k46 + POST rope arms branch-free via per-lane merged tables, 18 of 25 sections
# baseline (speedup 1.0000x reference)
; #define LAS __attribute__((address_space(3)))
; DI unsigned pk2(float lo, float hi) { f32x2 x = {lo, hi}; return __builtin_bit_cast(unsigned, __builtin_convertvector(x, bf16x2_t)); }
; DI float sum32(float v) { v += __shfl_xor(v, 16); return sum16(v); }
; DI f32x2 unpk(unsigned w) { f32x2 r = {bflo(w), bfhi(w)}; return r; }
; template <int HP> DI void rope2(f32x2& x, int hl, const LAS f32x2* cs) {
;   const float pa = __shfl_xor(x[0], HP), pb = __shfl_xor(x[1], HP);
;   if (hl < HP) { const f32x2 c0 = cs[2 * hl], c1 = cs[2 * hl + 1]; x[0] = x[0] * c0[0] - pa * c0[1]; x[1] = x[1] * c1[0] - pb * c1[1]; }
;   else if (hl < 2 * HP) { const f32x2 c0 = cs[2 * (hl - HP)], c1 = cs[2 * (hl - HP) + 1]; x[0] = x[0] * c0[0] + pa * c0[1]; x[1] = x[1] * c1[0] + pb * c1[1]; }
; }
; DI void post_unit(const Params& p, int l, int unit, LAS unsigned char* lds) {
;     ...
;   for (int tp = 0; tp < 4; ++tp) {
;     constexpr int segcol[16] = {C_QA, C_QA + 128, C_KA, C_QI, C_QI + 128, C_QI + 256, C_QI + 384, C_KI, C_QB, C_QB + 128, C_KB, C_KB + 128, C_QC, C_QC + 128, C_KC, C_KC + 128};
;     unsigned raw2[2][16];
; #pragma unroll
;     for (int hf = 0; hf < 2; ++hf) { const u16* rowl = proj + (tok0 + w * 8 + 2 * tp + hf) * NP;
; #pragma unroll
;       for (int s = 0; s < 16; ++s) raw2[hf][s] = *(const unsigned*)(rowl + segcol[s] + 2 * lane); }
; #pragma unroll
;     for (int hf = 0; hf < 2; ++hf) {
;     const int t = w * 8 + 2 * tp + hf; u16* row = proj + (tok0 + t) * NP;
; #pragma unroll
;     for (int s = 0; s < 16; ++s) {
;       f32x2 x = unpk(raw2[hf][s]); u16* pp = row + segcol[s] + 2 * lane;
;       if (s < 2) {
;         const float rs = rsqrtf(sum32(x[0] * x[0] + x[1] * x[1]) * (1.0f / 64.0f) + EPS);
;         x[0] *= rs * qna[2 * hl]; x[1] *= rs * qna[2 * hl + 1]; rope2<4>(x, hl, cs16 + t * 8);
;         x *= LOG2E * 0.125f; *(unsigned*)pp = pk2(x[0], x[1]);
.LBB0_150:
	ds_read_b128 v[208:211], v35
	ds_read_b128 v[212:215], v35 offset:64
	ds_read_b128 v[216:219], v39
	ds_read_b128 v[220:223], v39 offset:256
	ds_read_b128 v[224:227], v40
	ds_read_b128 v[228:231], v40 offset:32
	ds_read_b128 v[232:235], v35 offset:128
	ds_read_b128 v[236:239], v39 offset:512
	ds_read_b128 v[240:243], v40 offset:64
	s_waitcnt lgkmcnt(0)
	s_orn2_b64 s[98:99], s[14:15], s[12:13]
	s_orn2_b64 s[100:101], s[8:9], s[6:7]
	v_cndmask_b32_e64 v80, v212, v208, s[12:13]
	v_cndmask_b32_e64 v80, 1.0, v80, s[98:99]
	v_cndmask_b32_e64 v81, v214, v210, s[12:13]
	v_cndmask_b32_e64 v81, 1.0, v81, s[98:99]
	v_cndmask_b32_e64 v82, -v213, v209, s[12:13]
	v_cndmask_b32_e64 v82, 0, v82, s[98:99]
	v_cndmask_b32_e64 v83, -v215, v211, s[12:13]
	v_cndmask_b32_e64 v83, 0, v83, s[98:99]
	v_cndmask_b32_e64 v84, v220, v216, s[10:11]
	v_cndmask_b32_e64 v85, v222, v218, s[10:11]
	v_cndmask_b32_e64 v86, -v221, v217, s[10:11]
	v_cndmask_b32_e64 v87, -v223, v219, s[10:11]
	v_cndmask_b32_e64 v88, v228, v224, s[6:7]
	v_cndmask_b32_e64 v88, 1.0, v88, s[100:101]
	v_cndmask_b32_e64 v89, v230, v226, s[6:7]
	v_cndmask_b32_e64 v89, 1.0, v89, s[100:101]
	v_cndmask_b32_e64 v90, -v229, v225, s[6:7]
	v_cndmask_b32_e64 v90, 0, v90, s[100:101]
	v_cndmask_b32_e64 v91, -v231, v227, s[6:7]
	v_cndmask_b32_e64 v91, 0, v91, s[100:101]
	v_cndmask_b32_e64 v92, v232, v212, s[12:13]
	v_cndmask_b32_e64 v92, 1.0, v92, s[98:99]
	v_cndmask_b32_e64 v93, v234, v214, s[12:13]
	v_cndmask_b32_e64 v93, 1.0, v93, s[98:99]
	v_cndmask_b32_e64 v94, -v233, v213, s[12:13]
	v_cndmask_b32_e64 v94, 0, v94, s[98:99]
	v_cndmask_b32_e64 v95, -v235, v215, s[12:13]
	v_cndmask_b32_e64 v95, 0, v95, s[98:99]
	v_cndmask_b32_e64 v96, v240, v228, s[6:7]
	v_cndmask_b32_e64 v96, 1.0, v96, s[100:101]
	v_cndmask_b32_e64 v97, v242, v230, s[6:7]
	v_cndmask_b32_e64 v97, 1.0, v97, s[100:101]
	v_cndmask_b32_e64 v98, -v241, v229, s[6:7]
	v_cndmask_b32_e64 v98, 0, v98, s[100:101]
	v_cndmask_b32_e64 v99, -v243, v231, s[6:7]
	v_cndmask_b32_e64 v99, 0, v99, s[100:101]
	v_lshl_add_u64 v[18:19], v[12:13], 0, v[0:1]
	v_add_co_u32_e32 v20, vcc, 0xa000000, v18
	s_mov_b32 s2, 0xa001000
	s_waitcnt lgkmcnt(0)
	v_addc_co_u32_e32 v21, vcc, 0, v19, vcc
	global_load_dword v49, v[20:21], off
	v_add_co_u32_e32 v22, vcc, s2, v18
	s_mov_b32 s2, 0xa003000
	s_nop 0
	v_addc_co_u32_e32 v23, vcc, 0, v19, vcc
	v_add_co_u32_e32 v42, vcc, s77, v18
	global_load_dword v59, v[20:21], off offset:512
	global_load_dword v70, v[20:21], off offset:768
	global_load_dword v69, v[20:21], off offset:1024
	global_load_dword v68, v[20:21], off offset:1280
	global_load_dword v67, v[20:21], off offset:1536
	global_load_dword v58, v[20:21], off offset:1792
	global_load_dword v71, v[20:21], off offset:256
	v_addc_co_u32_e32 v43, vcc, 0, v19, vcc
	global_load_dword v56, v[20:21], off offset:2432
	global_load_dword v66, v[20:21], off offset:2688
	global_load_dword v65, v[20:21], off offset:2944
	global_load_dword v64, v[20:21], off offset:3200
	global_load_dword v54, v[22:23], off offset:384
	global_load_dword v63, v[22:23], off offset:640
	global_load_dword v62, v[22:23], off offset:896
	global_load_dword v61, v[22:23], off offset:1152
	v_add_co_u32_e32 v20, vcc, s2, v18
	global_load_dword v60, v[42:43], off offset:512
	global_load_dword v57, v[42:43], off offset:768
	global_load_dword v55, v[42:43], off offset:1024
	global_load_dword v53, v[42:43], off offset:1280
	global_load_dword v52, v[42:43], off offset:1536
	global_load_dword v51, v[42:43], off offset:1792
	global_load_dword v50, v[42:43], off offset:2048
	global_load_dword v48, v[42:43], off offset:2304
	v_addc_co_u32_e32 v21, vcc, 0, v19, vcc
	global_load_dword v47, v[42:43], off offset:2944
	global_load_dword v46, v[42:43], off offset:3200
	global_load_dword v45, v[42:43], off offset:3456
	global_load_dword v44, v[42:43], off offset:3712
	s_nop 0
	global_load_dword v43, v[20:21], off offset:896
	global_load_dword v42, v[20:21], off offset:1152
	global_load_dword v41, v[20:21], off offset:1408
	global_load_dword v3, v[20:21], off offset:1664
	s_waitcnt vmcnt(31)
	v_and_b32_e32 v21, 0xffff0000, v49
	v_lshlrev_b32_e32 v20, 16, v49
	v_pk_mul_f32 v[22:23], v[20:21], v[20:21]
	s_nop 0
	v_add_f32_e32 v22, v22, v23
	v_mov_b32_e32 v23, v22
	s_nop 1
	v_permlane16_swap_b32_e32 v22, v23
	v_add_f32_e32 v22, v22, v23
	s_nop 1
	v_add_f32_dpp v22, v22, v22 row_ror:8 row_mask:0xf bank_mask:0xf
	s_nop 1
	v_add_f32_dpp v22, v22, v22 row_ror:4 row_mask:0xf bank_mask:0xf
	s_nop 1
	v_add_f32_dpp v22, v22, v22 quad_perm:[2,3,0,1] row_mask:0xf bank_mask:0xf
	s_nop 1
	v_add_f32_dpp v22, v22, v22 quad_perm:[1,0,3,2] row_mask:0xf bank_mask:0xf
	v_fmamk_f32 v22, v22, 0x3c800000, v170
	v_mul_f32_e32 v23, 0x4b800000, v22
	v_cmp_gt_f32_e32 vcc, s33, v22
	s_nop 1
	v_cndmask_b32_e32 v22, v22, v23, vcc
	v_rsq_f32_e32 v22, v22
	s_nop 0
	v_mul_f32_e32 v23, 0x45800000, v22
	v_cndmask_b32_e32 v22, v22, v23, vcc
	v_pk_mul_f32 v[22:23], v[4:5], v[22:23] op_sel_hi:[1,0]
	s_nop 0
	v_pk_mul_f32 v[22:23], v[22:23], v[20:21]
	ds_bpermute_b32 v20, v28, v22
	ds_bpermute_b32 v21, v28, v23
	v_add_u32_e32 v49, 0, v35
	s_waitcnt lgkmcnt(0)
	v_mul_f32_e32 v22, v80, v22
	v_mul_f32_e32 v23, v81, v23
	v_fmac_f32_e32 v22, v82, v20
	v_fmac_f32_e32 v23, v83, v21
	s_mov_b64 s[2:3], 0xa000000
	s_waitcnt lgkmcnt(0)
	v_lshl_add_u64 v[20:21], v[18:19], 0, s[2:3]
	s_mov_b32 s2, 0x3e38aa3b
	v_pk_mul_f32 v[22:23], v[22:23], s[2:3] op_sel_hi:[1,0]
	s_nop 0
	v_cvt_pk_bf16_f32 v22, v22, v23
	global_store_dword v[20:21], v22, off
	s_waitcnt vmcnt(25)
; #define LAS __attribute__((address_space(3)))
; DI unsigned pk2(float lo, float hi) { f32x2 x = {lo, hi}; return __builtin_bit_cast(unsigned, __builtin_convertvector(x, bf16x2_t)); }
; DI float sum32(float v) { v += __shfl_xor(v, 16); return sum16(v); }
; DI float sum64(float v) { v += __shfl_xor(v, 32); return sum32(v); }
; DI f32x2 unpk(unsigned w) { f32x2 r = {bflo(w), bfhi(w)}; return r; }
; DI void post_unit(const Params& p, int l, int unit, LAS unsigned char* lds) {
;     ...
;     for (int s = 0; s < 16; ++s) {
;       f32x2 x = unpk(raw2[hf][s]); u16* pp = row + segcol[s] + 2 * lane;
;       if (s < 2) {
;         const float rs = rsqrtf(sum32(x[0] * x[0] + x[1] * x[1]) * (1.0f / 64.0f) + EPS);
;         x[0] *= rs * qna[2 * hl]; x[1] *= rs * qna[2 * hl + 1]; rope2<4>(x, hl, cs16 + t * 8);
;         x *= LOG2E * 0.125f; *(unsigned*)pp = pk2(x[0], x[1]);
;       } else if (s == 2) {
;         const float rs = rsqrtf(sum64(x[0] * x[0] + x[1] * x[1]) * (1.0f / 128.0f) + EPS);
;         *(LAS unsigned*)(At + t * 272 + lane * 4) = pk2(x[0] * rs, x[1] * rs);
;       } else if (s < 7) {
;         rope2<4>(x, hl, cs16 + t * 8); *(unsigned*)pp = pk2(x[0], x[1]);
;       } else if (s == 7) {
;         const float rs = rsqrtf(sum32(x[0] * x[0] + x[1] * x[1]) * (1.0f / 64.0f) + EPS);
;         x *= rs; rope2<4>(x, hl, cs16 + t * 8); if (lane < 32) *(unsigned*)((u16*)(p.ws + WS_KIC) + (tok0 + t) * 64 + 2 * lane) = pk2(x[0], x[1]);
	v_and_b32_e32 v21, 0xffff0000, v71
	v_lshlrev_b32_e32 v20, 16, v71
	v_pk_mul_f32 v[22:23], v[20:21], v[20:21]
	s_nop 0
	v_add_f32_e32 v22, v22, v23
	v_mov_b32_e32 v23, v22
	s_nop 1
	v_permlane16_swap_b32_e32 v22, v23
	v_add_f32_e32 v22, v22, v23
	s_nop 1
	v_add_f32_dpp v22, v22, v22 row_ror:8 row_mask:0xf bank_mask:0xf
	s_nop 1
	v_add_f32_dpp v22, v22, v22 row_ror:4 row_mask:0xf bank_mask:0xf
	s_nop 1
	v_add_f32_dpp v22, v22, v22 quad_perm:[2,3,0,1] row_mask:0xf bank_mask:0xf
	s_nop 1
	v_add_f32_dpp v22, v22, v22 quad_perm:[1,0,3,2] row_mask:0xf bank_mask:0xf
	v_fmamk_f32 v22, v22, 0x3c800000, v170
	v_cmp_gt_f32_e32 vcc, s33, v22
	v_mul_f32_e32 v23, 0x4b800000, v22
	s_nop 0
	v_cndmask_b32_e32 v22, v22, v23, vcc
	v_rsq_f32_e32 v22, v22
	s_nop 0
	v_mul_f32_e32 v23, 0x45800000, v22
	v_cndmask_b32_e32 v22, v22, v23, vcc
	v_pk_mul_f32 v[22:23], v[4:5], v[22:23] op_sel_hi:[1,0]
	s_nop 0
	v_pk_mul_f32 v[22:23], v[22:23], v[20:21]
	ds_bpermute_b32 v20, v28, v22
	ds_bpermute_b32 v21, v28, v23
	s_waitcnt lgkmcnt(0)
	v_mul_f32_e32 v22, v80, v22
	v_mul_f32_e32 v23, v81, v23
	v_fmac_f32_e32 v22, v82, v20
	v_fmac_f32_e32 v23, v83, v21
	s_mov_b64 s[2:3], 0xa000100
	s_waitcnt lgkmcnt(0)
	v_lshl_add_u64 v[20:21], v[18:19], 0, s[2:3]
	s_mov_b32 s2, 0x3e38aa3b
	v_pk_mul_f32 v[22:23], v[22:23], s[2:3] op_sel_hi:[1,0]
	s_nop 0
	v_cvt_pk_bf16_f32 v22, v22, v23
	global_store_dword v[20:21], v22, off
	v_lshlrev_b32_e32 v20, 16, v59
	v_and_b32_e32 v21, 0xffff0000, v59
	v_pk_mul_f32 v[22:23], v[20:21], v[20:21]
	v_add_u32_e32 v59, 0, v33
	v_add_f32_e32 v22, v22, v23
	v_mov_b32_e32 v23, v22
	s_nop 1
	v_permlane32_swap_b32_e32 v22, v23
	v_add_f32_e32 v22, v22, v23
	v_mov_b32_e32 v23, v22
	s_nop 1
	v_permlane16_swap_b32_e32 v22, v23
	v_add_f32_e32 v22, v22, v23
	s_nop 1
	v_add_f32_dpp v22, v22, v22 row_ror:8 row_mask:0xf bank_mask:0xf
	s_nop 1
	v_add_f32_dpp v22, v22, v22 row_ror:4 row_mask:0xf bank_mask:0xf
	s_nop 1
	v_add_f32_dpp v22, v22, v22 quad_perm:[2,3,0,1] row_mask:0xf bank_mask:0xf
	s_nop 1
	v_add_f32_dpp v22, v22, v22 quad_perm:[1,0,3,2] row_mask:0xf bank_mask:0xf
	v_fmamk_f32 v22, v22, 0x3c000000, v170
	v_cmp_gt_f32_e32 vcc, s33, v22
	v_mul_f32_e32 v23, 0x4b800000, v22
	s_nop 0
	v_cndmask_b32_e32 v22, v22, v23, vcc
	v_rsq_f32_e32 v22, v22
	s_nop 0
	v_mul_f32_e32 v23, 0x45800000, v22
	v_cndmask_b32_e32 v22, v22, v23, vcc
	v_pk_mul_f32 v[20:21], v[22:23], v[20:21] op_sel_hi:[0,1]
	v_cvt_pk_bf16_f32 v20, v20, v21
	ds_write_b32 v59, v20
	v_lshlrev_b32_e32 v20, 16, v70
	v_and_b32_e32 v21, 0xffff0000, v70
	ds_bpermute_b32 v70, v28, v20
	ds_bpermute_b32 v23, v28, v21
	s_waitcnt lgkmcnt(0)
	v_mul_f32_e32 v20, v80, v20
	v_mul_f32_e32 v21, v81, v21
	v_fmac_f32_e32 v20, v82, v70
	v_fmac_f32_e32 v21, v83, v23
	s_mov_b64 s[2:3], 0xa000300
	s_waitcnt lgkmcnt(0)
	v_lshl_add_u64 v[22:23], v[18:19], 0, s[2:3]
	v_cvt_pk_bf16_f32 v20, v20, v21
	global_store_dword v[22:23], v20, off
	v_lshlrev_b32_e32 v20, 16, v69
	v_and_b32_e32 v21, 0xffff0000, v69
	ds_bpermute_b32 v69, v28, v20
	ds_bpermute_b32 v23, v28, v21
	s_waitcnt lgkmcnt(0)
	v_mul_f32_e32 v20, v80, v20
	v_mul_f32_e32 v21, v81, v21
	v_fmac_f32_e32 v20, v82, v69
	v_fmac_f32_e32 v21, v83, v23
	s_mov_b64 s[2:3], 0xa000400
	s_waitcnt lgkmcnt(0)
	v_lshl_add_u64 v[22:23], v[18:19], 0, s[2:3]
	v_cvt_pk_bf16_f32 v20, v20, v21
	global_store_dword v[22:23], v20, off
	v_lshlrev_b32_e32 v20, 16, v68
	v_and_b32_e32 v21, 0xffff0000, v68
	ds_bpermute_b32 v68, v28, v20
	ds_bpermute_b32 v23, v28, v21
	s_waitcnt lgkmcnt(0)
	v_mul_f32_e32 v20, v80, v20
	v_mul_f32_e32 v21, v81, v21
	v_fmac_f32_e32 v20, v82, v68
	v_fmac_f32_e32 v21, v83, v23
	s_mov_b64 s[2:3], 0xa000500
	s_waitcnt lgkmcnt(0)
	v_lshl_add_u64 v[22:23], v[18:19], 0, s[2:3]
	v_cvt_pk_bf16_f32 v20, v20, v21
	global_store_dword v[22:23], v20, off
	v_lshlrev_b32_e32 v20, 16, v67
	v_and_b32_e32 v21, 0xffff0000, v67
	ds_bpermute_b32 v67, v28, v20
	ds_bpermute_b32 v23, v28, v21
	s_waitcnt lgkmcnt(0)
	v_mul_f32_e32 v20, v80, v20
	v_mul_f32_e32 v21, v81, v21
	v_fmac_f32_e32 v20, v82, v67
	v_fmac_f32_e32 v21, v83, v23
	s_mov_b64 s[2:3], 0xa000600
	s_waitcnt lgkmcnt(0)
	v_lshl_add_u64 v[22:23], v[18:19], 0, s[2:3]
	v_cvt_pk_bf16_f32 v20, v20, v21
	global_store_dword v[22:23], v20, off
	v_lshlrev_b32_e32 v20, 16, v58
	v_and_b32_e32 v21, 0xffff0000, v58
	v_pk_mul_f32 v[22:23], v[20:21], v[20:21]
	s_nop 0
	v_add_f32_e32 v22, v22, v23
	v_mov_b32_e32 v23, v22
	s_nop 1
	v_permlane16_swap_b32_e32 v22, v23
	v_add_f32_e32 v22, v22, v23
	s_nop 1
	v_add_f32_dpp v22, v22, v22 row_ror:8 row_mask:0xf bank_mask:0xf
	s_nop 1
	v_add_f32_dpp v22, v22, v22 row_ror:4 row_mask:0xf bank_mask:0xf
	s_nop 1
	v_add_f32_dpp v22, v22, v22 quad_perm:[2,3,0,1] row_mask:0xf bank_mask:0xf
	s_nop 1
	v_add_f32_dpp v22, v22, v22 quad_perm:[1,0,3,2] row_mask:0xf bank_mask:0xf
	v_fmamk_f32 v22, v22, 0x3c800000, v170
	v_cmp_gt_f32_e32 vcc, s33, v22
	v_mul_f32_e32 v23, 0x4b800000, v22
	s_nop 0
	v_cndmask_b32_e32 v22, v22, v23, vcc
	v_rsq_f32_e32 v22, v22
	s_nop 0
	v_mul_f32_e32 v23, 0x45800000, v22
	v_cndmask_b32_e32 v22, v22, v23, vcc
	v_pk_mul_f32 v[20:21], v[22:23], v[20:21] op_sel_hi:[0,1]
	ds_bpermute_b32 v22, v28, v20
	ds_bpermute_b32 v23, v28, v21
	s_and_saveexec_b64 s[2:3], s[12:13]
	s_xor_b64 s[18:19], exec, s[2:3]
	s_cbranch_execz .LBB0_314
	s_and_saveexec_b64 s[30:31], s[14:15]
	s_cbranch_execz .LBB0_189
	s_waitcnt lgkmcnt(0)
	v_mul_f32_e32 v20, v20, v208
	v_mul_f32_e32 v21, v210, v21
	v_fmac_f32_e32 v20, v209, v22
	v_fmac_f32_e32 v21, v211, v23

; DI unsigned pk2(float lo, float hi) { f32x2 x = {lo, hi}; return __builtin_bit_cast(unsigned, __builtin_convertvector(x, bf16x2_t)); }
; DI float sum16(float v) { v += __shfl_xor(v, 8); v += __shfl_xor(v, 4); v += __shfl_xor(v, 2); v += __shfl_xor(v, 1); return v; }
; DI void post_unit(const Params& p, int l, int unit, LAS unsigned char* lds) {
;     ...
;       } else if (s < 12) {
;         rope2<16>(x, hl, cs64 + t * 32);
;         const int hd = ((s & 1) ? 2 : 0) + hsel;
;         const float lg = log1pf(-exp2f(-5.0f - (float)hd));
;         const float f = (s < 10) ? expf(lg * (float)(t + 1)) : expf(lg * (float)(63 - t)) * 0.125f;
;         x *= f; *(unsigned*)pp = pk2(x[0], x[1]);
;       } else {
;         const float* gn = (s < 14) ? qnc : knc;
;         const float rs = rsqrtf(sum16(x[0] * x[0] + x[1] * x[1]) * (1.0f / 32.0f) + EPS);
;         x[0] *= rs * gn[2 * hl16]; x[1] *= rs * gn[2 * hl16 + 1]; rope2<2>(x, hl16, cs8 + t * 4);
;         if (s < 14) x *= LOG2E * 0.17677669529663687f;
;         *(unsigned*)pp = pk2(x[0], x[1]);
.LBB0_196:
	s_or_b64 exec, exec, s[18:19]
	v_add_u32_e32 v58, s36, v2
	s_waitcnt lgkmcnt(1)
	v_add_u32_e32 v67, 1, v58
	v_cvt_f32_i32_e32 v67, v67
	s_mov_b64 s[2:3], 0xa000980
	s_waitcnt lgkmcnt(0)
	v_lshl_add_u64 v[22:23], v[18:19], 0, s[2:3]
	v_mul_f32_e32 v68, v31, v67
	v_mul_f32_e32 v69, 0x3fb8aa3b, v68
	v_fma_f32 v70, v68, s64, -v69
	v_rndne_f32_e32 v71, v69
	v_fmac_f32_e32 v70, 0x32a5705f, v68
	v_sub_f32_e32 v69, v69, v71
	v_add_f32_e32 v69, v69, v70
	v_exp_f32_e32 v69, v69
	v_cvt_i32_f32_e32 v70, v71
	v_cmp_ngt_f32_e32 vcc, s65, v68
	v_ldexp_f32 v69, v69, v70
	s_nop 0
	v_cndmask_b32_e32 v69, 0, v69, vcc
	v_cmp_nlt_f32_e32 vcc, s89, v68
	s_nop 1
	v_cndmask_b32_e32 v68, v177, v69, vcc
	v_pk_mul_f32 v[20:21], v[68:69], v[20:21] op_sel_hi:[0,1]
	v_cvt_pk_bf16_f32 v20, v20, v21
	global_store_dword v[22:23], v20, off
	s_waitcnt vmcnt(29)
	v_lshlrev_b32_e32 v68, 16, v66
	v_and_b32_e32 v20, 0xffff0000, v66
	ds_bpermute_b32 v66, v26, v68
	ds_bpermute_b32 v21, v26, v20
	s_waitcnt lgkmcnt(0)
	v_mul_f32_e32 v22, v84, v68
	v_mul_f32_e32 v23, v85, v20
	v_fmac_f32_e32 v22, v86, v66
	v_fmac_f32_e32 v23, v87, v21
	s_waitcnt lgkmcnt(1)
	v_mul_f32_e32 v66, v32, v67
	v_mul_f32_e32 v67, 0x3fb8aa3b, v66
	v_fma_f32 v68, v66, s64, -v67
	v_rndne_f32_e32 v69, v67
	v_fmac_f32_e32 v68, 0x32a5705f, v66
	v_sub_f32_e32 v67, v67, v69
	v_add_f32_e32 v67, v67, v68
	v_exp_f32_e32 v67, v67
	v_cvt_i32_f32_e32 v68, v69
	v_cmp_ngt_f32_e32 vcc, s65, v66
	s_mov_b64 s[2:3], 0xa000a80
	s_waitcnt lgkmcnt(0)
	v_lshl_add_u64 v[20:21], v[18:19], 0, s[2:3]
	v_ldexp_f32 v67, v67, v68
	v_cndmask_b32_e32 v67, 0, v67, vcc
	v_cmp_nlt_f32_e32 vcc, s89, v66
	s_nop 1
	v_cndmask_b32_e32 v66, v177, v67, vcc
	v_pk_mul_f32 v[22:23], v[66:67], v[22:23] op_sel_hi:[0,1]
	v_cvt_pk_bf16_f32 v22, v22, v23
	global_store_dword v[20:21], v22, off
	s_waitcnt vmcnt(29)
	v_lshlrev_b32_e32 v66, 16, v65
	v_and_b32_e32 v22, 0xffff0000, v65
	ds_bpermute_b32 v65, v26, v66
	ds_bpermute_b32 v23, v26, v22
	s_waitcnt lgkmcnt(0)
	v_mul_f32_e32 v20, v84, v66
	v_mul_f32_e32 v21, v85, v22
	v_fmac_f32_e32 v20, v86, v65
	v_fmac_f32_e32 v21, v87, v23
	s_waitcnt lgkmcnt(1)
	v_add_u32_e32 v65, 1, v38
	v_cvt_f32_i32_e32 v65, v65
	s_mov_b64 s[2:3], 0xa000b80
	s_waitcnt lgkmcnt(0)
	v_lshl_add_u64 v[22:23], v[18:19], 0, s[2:3]
	v_mul_f32_e32 v66, v31, v65
	v_mul_f32_e32 v67, 0x3fb8aa3b, v66
	v_fma_f32 v68, v66, s64, -v67
	v_rndne_f32_e32 v69, v67
	v_fmac_f32_e32 v68, 0x32a5705f, v66
	v_sub_f32_e32 v67, v67, v69
	v_add_f32_e32 v67, v67, v68
	v_exp_f32_e32 v67, v67
	v_cvt_i32_f32_e32 v68, v69
	v_cmp_ngt_f32_e32 vcc, s65, v66
	v_ldexp_f32 v67, v67, v68
	s_nop 0
	v_cndmask_b32_e32 v67, 0, v67, vcc
	v_cmp_nlt_f32_e32 vcc, s89, v66
	s_nop 1
	v_cndmask_b32_e32 v66, v177, v67, vcc
	v_mul_f32_e32 v66, 0x3e000000, v66
	v_pk_mul_f32 v[20:21], v[66:67], v[20:21] op_sel_hi:[0,1]
	v_cvt_pk_bf16_f32 v20, v20, v21
	global_store_dword v[22:23], v20, off
	s_waitcnt vmcnt(29)
	v_lshlrev_b32_e32 v66, 16, v64
	v_and_b32_e32 v20, 0xffff0000, v64
	ds_bpermute_b32 v64, v26, v66
	ds_bpermute_b32 v21, v26, v20
	s_waitcnt lgkmcnt(0)
	v_mul_f32_e32 v22, v84, v66
	v_mul_f32_e32 v23, v85, v20
	v_fmac_f32_e32 v22, v86, v64
	v_fmac_f32_e32 v23, v87, v21
	s_waitcnt lgkmcnt(1)
	v_mul_f32_e32 v64, v32, v65
	v_mul_f32_e32 v65, 0x3fb8aa3b, v64
	v_fma_f32 v66, v64, s64, -v65
	v_rndne_f32_e32 v67, v65
	v_fmac_f32_e32 v66, 0x32a5705f, v64
	v_sub_f32_e32 v65, v65, v67
	v_add_f32_e32 v65, v65, v66
	v_exp_f32_e32 v65, v65
	v_cvt_i32_f32_e32 v66, v67
	v_cmp_ngt_f32_e32 vcc, s65, v64
	s_mov_b64 s[2:3], 0xa000c80
	s_waitcnt lgkmcnt(0)
	v_lshl_add_u64 v[20:21], v[18:19], 0, s[2:3]
	v_ldexp_f32 v65, v65, v66
	v_cndmask_b32_e32 v65, 0, v65, vcc
	v_cmp_nlt_f32_e32 vcc, s89, v64
	s_nop 1
	v_cndmask_b32_e32 v64, v177, v65, vcc
	v_mul_f32_e32 v64, 0x3e000000, v64
	v_pk_mul_f32 v[22:23], v[64:65], v[22:23] op_sel_hi:[0,1]
	v_cvt_pk_bf16_f32 v22, v22, v23
	global_store_dword v[20:21], v22, off
	s_waitcnt vmcnt(29)
	v_lshlrev_b32_e32 v20, 16, v54
	v_and_b32_e32 v21, 0xffff0000, v54
	v_pk_mul_f32 v[22:23], v[20:21], v[20:21]
	s_nop 0
	v_add_f32_e32 v22, v22, v23
	s_nop 1
	v_add_f32_dpp v22, v22, v22 row_ror:8 row_mask:0xf bank_mask:0xf
	s_nop 1
	v_add_f32_dpp v22, v22, v22 row_ror:4 row_mask:0xf bank_mask:0xf
	s_nop 1
	v_add_f32_dpp v22, v22, v22 quad_perm:[2,3,0,1] row_mask:0xf bank_mask:0xf
	s_nop 1
	v_add_f32_dpp v22, v22, v22 quad_perm:[1,0,3,2] row_mask:0xf bank_mask:0xf
	v_fmamk_f32 v22, v22, 0x3d000000, v170
	v_cmp_gt_f32_e32 vcc, s33, v22
	v_mul_f32_e32 v23, 0x4b800000, v22
	s_nop 0
	v_cndmask_b32_e32 v22, v22, v23, vcc
	v_rsq_f32_e32 v22, v22
	s_nop 0
	v_mul_f32_e32 v23, 0x45800000, v22
	v_cndmask_b32_e32 v22, v22, v23, vcc
	v_pk_mul_f32 v[22:23], v[6:7], v[22:23] op_sel_hi:[1,0]
	s_nop 0
	v_pk_mul_f32 v[22:23], v[22:23], v[20:21]
	ds_bpermute_b32 v20, v29, v22
	ds_bpermute_b32 v21, v29, v23
	v_add_u32_e32 v54, 0, v40
	s_waitcnt lgkmcnt(0)
	v_mul_f32_e32 v22, v88, v22
	v_mul_f32_e32 v23, v89, v23
	v_fmac_f32_e32 v22, v90, v20
	v_fmac_f32_e32 v23, v91, v21
	s_mov_b64 s[2:3], 0xa001180
	s_waitcnt lgkmcnt(0)
	v_lshl_add_u64 v[20:21], v[18:19], 0, s[2:3]
	s_mov_b32 s2, 0x3e8293ee
	v_pk_mul_f32 v[22:23], v[22:23], s[2:3] op_sel_hi:[1,0]
	s_nop 0
	v_cvt_pk_bf16_f32 v22, v22, v23
	global_store_dword v[20:21], v22, off
	s_waitcnt vmcnt(29)
; DI unsigned pk2(float lo, float hi) { f32x2 x = {lo, hi}; return __builtin_bit_cast(unsigned, __builtin_convertvector(x, bf16x2_t)); }
; DI float sum16(float v) { v += __shfl_xor(v, 8); v += __shfl_xor(v, 4); v += __shfl_xor(v, 2); v += __shfl_xor(v, 1); return v; }
; DI float sum32(float v) { v += __shfl_xor(v, 16); return sum16(v); }
; DI f32x2 unpk(unsigned w) { f32x2 r = {bflo(w), bfhi(w)}; return r; }
; DI void post_unit(const Params& p, int l, int unit, LAS unsigned char* lds) {
;     ...
;     for (int s = 0; s < 16; ++s) {
;       f32x2 x = unpk(raw2[hf][s]); u16* pp = row + segcol[s] + 2 * lane;
;       if (s < 2) {
;         const float rs = rsqrtf(sum32(x[0] * x[0] + x[1] * x[1]) * (1.0f / 64.0f) + EPS);
;         x[0] *= rs * qna[2 * hl]; x[1] *= rs * qna[2 * hl + 1]; rope2<4>(x, hl, cs16 + t * 8);
;         x *= LOG2E * 0.125f; *(unsigned*)pp = pk2(x[0], x[1]);
;     ...
;       } else {
;         const float* gn = (s < 14) ? qnc : knc;
;         const float rs = rsqrtf(sum16(x[0] * x[0] + x[1] * x[1]) * (1.0f / 32.0f) + EPS);
;         x[0] *= rs * gn[2 * hl16]; x[1] *= rs * gn[2 * hl16 + 1]; rope2<2>(x, hl16, cs8 + t * 4);
;         if (s < 14) x *= LOG2E * 0.17677669529663687f;
;         *(unsigned*)pp = pk2(x[0], x[1]);
	v_lshlrev_b32_e32 v20, 16, v63
	v_and_b32_e32 v21, 0xffff0000, v63
	v_pk_mul_f32 v[22:23], v[20:21], v[20:21]
	s_nop 0
	v_add_f32_e32 v22, v22, v23
	s_nop 1
	v_add_f32_dpp v22, v22, v22 row_ror:8 row_mask:0xf bank_mask:0xf
	s_nop 1
	v_add_f32_dpp v22, v22, v22 row_ror:4 row_mask:0xf bank_mask:0xf
	s_nop 1
	v_add_f32_dpp v22, v22, v22 quad_perm:[2,3,0,1] row_mask:0xf bank_mask:0xf
	s_nop 1
	v_add_f32_dpp v22, v22, v22 quad_perm:[1,0,3,2] row_mask:0xf bank_mask:0xf
	v_fmamk_f32 v22, v22, 0x3d000000, v170
	v_cmp_gt_f32_e32 vcc, s33, v22
	v_mul_f32_e32 v23, 0x4b800000, v22
	s_nop 0
	v_cndmask_b32_e32 v22, v22, v23, vcc
	v_rsq_f32_e32 v22, v22
	s_nop 0
	v_mul_f32_e32 v23, 0x45800000, v22
	v_cndmask_b32_e32 v22, v22, v23, vcc
	v_pk_mul_f32 v[22:23], v[6:7], v[22:23] op_sel_hi:[1,0]
	s_nop 0
	v_pk_mul_f32 v[22:23], v[22:23], v[20:21]
	ds_bpermute_b32 v20, v29, v22
	ds_bpermute_b32 v21, v29, v23
	s_waitcnt lgkmcnt(0)
	v_mul_f32_e32 v22, v88, v22
	v_mul_f32_e32 v23, v89, v23
	v_fmac_f32_e32 v22, v90, v20
	v_fmac_f32_e32 v23, v91, v21
	s_mov_b64 s[2:3], 0xa001280
	s_waitcnt lgkmcnt(0)
	v_lshl_add_u64 v[20:21], v[18:19], 0, s[2:3]
	s_mov_b32 s2, 0x3e8293ee
	v_pk_mul_f32 v[22:23], v[22:23], s[2:3] op_sel_hi:[1,0]
	s_nop 0
	v_cvt_pk_bf16_f32 v22, v22, v23
	global_store_dword v[20:21], v22, off
	s_waitcnt vmcnt(29)
	v_lshlrev_b32_e32 v20, 16, v62
	v_and_b32_e32 v21, 0xffff0000, v62
	v_pk_mul_f32 v[22:23], v[20:21], v[20:21]
	s_nop 0
	v_add_f32_e32 v22, v22, v23
	s_nop 1
	v_add_f32_dpp v22, v22, v22 row_ror:8 row_mask:0xf bank_mask:0xf
	s_nop 1
	v_add_f32_dpp v22, v22, v22 row_ror:4 row_mask:0xf bank_mask:0xf
	s_nop 1
	v_add_f32_dpp v22, v22, v22 quad_perm:[2,3,0,1] row_mask:0xf bank_mask:0xf
	s_nop 1
	v_add_f32_dpp v22, v22, v22 quad_perm:[1,0,3,2] row_mask:0xf bank_mask:0xf
	v_fmamk_f32 v22, v22, 0x3d000000, v170
	v_cmp_gt_f32_e32 vcc, s33, v22
	v_mul_f32_e32 v23, 0x4b800000, v22
	s_nop 0
	v_cndmask_b32_e32 v22, v22, v23, vcc
	v_rsq_f32_e32 v22, v22
	s_nop 0
	v_mul_f32_e32 v23, 0x45800000, v22
	v_cndmask_b32_e32 v22, v22, v23, vcc
	v_pk_mul_f32 v[22:23], v[8:9], v[22:23] op_sel_hi:[1,0]
	s_nop 0
	v_pk_mul_f32 v[22:23], v[22:23], v[20:21]
	ds_bpermute_b32 v20, v29, v22
	ds_bpermute_b32 v21, v29, v23
	s_waitcnt lgkmcnt(0)
	v_mul_f32_e32 v22, v88, v22
	v_mul_f32_e32 v23, v89, v23
	v_fmac_f32_e32 v22, v90, v20
	v_fmac_f32_e32 v23, v91, v21
	s_mov_b64 s[2:3], 0xa001380
	s_waitcnt lgkmcnt(0)
	v_lshl_add_u64 v[20:21], v[18:19], 0, s[2:3]
	v_cvt_pk_bf16_f32 v22, v22, v23
	global_store_dword v[20:21], v22, off
	s_waitcnt vmcnt(29)
	v_lshlrev_b32_e32 v20, 16, v61
	v_and_b32_e32 v21, 0xffff0000, v61
	v_pk_mul_f32 v[22:23], v[20:21], v[20:21]
	s_nop 0
	v_add_f32_e32 v22, v22, v23
	s_nop 1
	v_add_f32_dpp v22, v22, v22 row_ror:8 row_mask:0xf bank_mask:0xf
	s_nop 1
	v_add_f32_dpp v22, v22, v22 row_ror:4 row_mask:0xf bank_mask:0xf
	s_nop 1
	v_add_f32_dpp v22, v22, v22 quad_perm:[2,3,0,1] row_mask:0xf bank_mask:0xf
	s_nop 1
	v_add_f32_dpp v22, v22, v22 quad_perm:[1,0,3,2] row_mask:0xf bank_mask:0xf
	v_fmamk_f32 v22, v22, 0x3d000000, v170
	v_cmp_gt_f32_e32 vcc, s33, v22
	v_mul_f32_e32 v23, 0x4b800000, v22
	s_nop 0
	v_cndmask_b32_e32 v22, v22, v23, vcc
	v_rsq_f32_e32 v22, v22
	s_nop 0
	v_mul_f32_e32 v23, 0x45800000, v22
	v_cndmask_b32_e32 v22, v22, v23, vcc
	v_pk_mul_f32 v[22:23], v[8:9], v[22:23] op_sel_hi:[1,0]
	s_nop 0
	v_pk_mul_f32 v[22:23], v[22:23], v[20:21]
	ds_bpermute_b32 v20, v29, v22
	ds_bpermute_b32 v21, v29, v23
	s_waitcnt lgkmcnt(0)
	v_mul_f32_e32 v22, v88, v22
	v_mul_f32_e32 v23, v89, v23
	v_fmac_f32_e32 v22, v90, v20
	v_fmac_f32_e32 v23, v91, v21
	s_mov_b64 s[2:3], 0xa001480
	v_lshl_add_u64 v[18:19], v[18:19], 0, s[2:3]
	s_waitcnt lgkmcnt(1)
	v_cvt_pk_bf16_f32 v20, v22, v23
	global_store_dword v[18:19], v20, off
	s_waitcnt vmcnt(29)
	v_and_b32_e32 v19, 0xffff0000, v60
	v_lshlrev_b32_e32 v18, 16, v60
	s_waitcnt lgkmcnt(0)
	v_pk_mul_f32 v[20:21], v[18:19], v[18:19]
	s_nop 0
	v_add_f32_e32 v20, v20, v21
	v_mov_b32_e32 v21, v20
	s_nop 1
	v_permlane16_swap_b32_e32 v20, v21
	v_add_f32_e32 v20, v20, v21
	s_nop 1
	v_add_f32_dpp v20, v20, v20 row_ror:8 row_mask:0xf bank_mask:0xf
	s_nop 1
	v_add_f32_dpp v20, v20, v20 row_ror:4 row_mask:0xf bank_mask:0xf
	s_nop 1
	v_add_f32_dpp v20, v20, v20 quad_perm:[2,3,0,1] row_mask:0xf bank_mask:0xf
	s_nop 1
	v_add_f32_dpp v20, v20, v20 quad_perm:[1,0,3,2] row_mask:0xf bank_mask:0xf
	v_fmamk_f32 v20, v20, 0x3c800000, v170
	v_cmp_gt_f32_e32 vcc, s33, v20
	v_mul_f32_e32 v21, 0x4b800000, v20
	s_nop 0
	v_cndmask_b32_e32 v20, v20, v21, vcc
	v_rsq_f32_e32 v20, v20
	s_nop 0
	v_mul_f32_e32 v21, 0x45800000, v20
	v_cndmask_b32_e32 v20, v20, v21, vcc
	v_pk_mul_f32 v[20:21], v[4:5], v[20:21] op_sel_hi:[1,0]
	s_nop 0
	v_pk_mul_f32 v[20:21], v[20:21], v[18:19]
	ds_bpermute_b32 v18, v28, v20
	ds_bpermute_b32 v19, v28, v21
	s_waitcnt lgkmcnt(0)
; #define LAS __attribute__((address_space(3)))
; DI unsigned pk2(float lo, float hi) { f32x2 x = {lo, hi}; return __builtin_bit_cast(unsigned, __builtin_convertvector(x, bf16x2_t)); }
; DI float sum32(float v) { v += __shfl_xor(v, 16); return sum16(v); }
; DI float sum64(float v) { v += __shfl_xor(v, 32); return sum32(v); }
; DI f32x2 unpk(unsigned w) { f32x2 r = {bflo(w), bfhi(w)}; return r; }
; DI void post_unit(const Params& p, int l, int unit, LAS unsigned char* lds) {
;     ...
;     for (int s = 0; s < 16; ++s) {
;       f32x2 x = unpk(raw2[hf][s]); u16* pp = row + segcol[s] + 2 * lane;
;       if (s < 2) {
;         const float rs = rsqrtf(sum32(x[0] * x[0] + x[1] * x[1]) * (1.0f / 64.0f) + EPS);
;         x[0] *= rs * qna[2 * hl]; x[1] *= rs * qna[2 * hl + 1]; rope2<4>(x, hl, cs16 + t * 8);
;         x *= LOG2E * 0.125f; *(unsigned*)pp = pk2(x[0], x[1]);
;       } else if (s == 2) {
;         const float rs = rsqrtf(sum64(x[0] * x[0] + x[1] * x[1]) * (1.0f / 128.0f) + EPS);
;         *(LAS unsigned*)(At + t * 272 + lane * 4) = pk2(x[0] * rs, x[1] * rs);
;       } else if (s < 7) {
;         rope2<4>(x, hl, cs16 + t * 8); *(unsigned*)pp = pk2(x[0], x[1]);
	v_mul_f32_e32 v20, v92, v20
	v_mul_f32_e32 v21, v93, v21
	v_fmac_f32_e32 v20, v94, v18
	v_fmac_f32_e32 v21, v95, v19
	s_mov_b32 s2, 0x3e38aa3b
	s_waitcnt lgkmcnt(0)
	v_lshl_add_u64 v[18:19], v[14:15], 0, v[0:1]
	v_pk_mul_f32 v[20:21], v[20:21], s[2:3] op_sel_hi:[1,0]
	s_nop 0
	v_cvt_pk_bf16_f32 v22, v20, v21
	v_add_co_u32_e32 v20, vcc, 0xa002000, v18
	s_nop 1
	v_addc_co_u32_e32 v21, vcc, 0, v19, vcc
	global_store_dword v[20:21], v22, off offset:512
	s_waitcnt vmcnt(29)
	v_and_b32_e32 v21, 0xffff0000, v57
	v_lshlrev_b32_e32 v20, 16, v57
	v_pk_mul_f32 v[22:23], v[20:21], v[20:21]
	s_nop 0
	v_add_f32_e32 v22, v22, v23
	v_mov_b32_e32 v23, v22
	s_nop 1
	v_permlane16_swap_b32_e32 v22, v23
	v_add_f32_e32 v22, v22, v23
	s_nop 1
	v_add_f32_dpp v22, v22, v22 row_ror:8 row_mask:0xf bank_mask:0xf
	s_nop 1
	v_add_f32_dpp v22, v22, v22 row_ror:4 row_mask:0xf bank_mask:0xf
	s_nop 1
	v_add_f32_dpp v22, v22, v22 quad_perm:[2,3,0,1] row_mask:0xf bank_mask:0xf
	s_nop 1
	v_add_f32_dpp v22, v22, v22 quad_perm:[1,0,3,2] row_mask:0xf bank_mask:0xf
	v_fmamk_f32 v22, v22, 0x3c800000, v170
	v_cmp_gt_f32_e32 vcc, s33, v22
	v_mul_f32_e32 v23, 0x4b800000, v22
	s_nop 0
	v_cndmask_b32_e32 v22, v22, v23, vcc
	v_rsq_f32_e32 v22, v22
	s_nop 0
	v_mul_f32_e32 v23, 0x45800000, v22
	v_cndmask_b32_e32 v22, v22, v23, vcc
	v_pk_mul_f32 v[22:23], v[4:5], v[22:23] op_sel_hi:[1,0]
	s_nop 0
	v_pk_mul_f32 v[22:23], v[22:23], v[20:21]
	ds_bpermute_b32 v20, v28, v22
	ds_bpermute_b32 v21, v28, v23
	s_waitcnt lgkmcnt(0)
	v_mul_f32_e32 v22, v92, v22
	v_mul_f32_e32 v23, v93, v23
	v_fmac_f32_e32 v22, v94, v20
	v_fmac_f32_e32 v23, v95, v21
	s_mov_b32 s2, 0x3e38aa3b
	s_waitcnt lgkmcnt(0)
	v_pk_mul_f32 v[20:21], v[22:23], s[2:3] op_sel_hi:[1,0]
	s_nop 0
	v_cvt_pk_bf16_f32 v22, v20, v21
	v_add_co_u32_e32 v20, vcc, 0xa002000, v18
	s_nop 1
	v_addc_co_u32_e32 v21, vcc, 0, v19, vcc
	global_store_dword v[20:21], v22, off offset:768
	s_waitcnt vmcnt(29)
	v_lshlrev_b32_e32 v20, 16, v55
	v_and_b32_e32 v21, 0xffff0000, v55
	v_pk_mul_f32 v[22:23], v[20:21], v[20:21]
	s_nop 0
	v_add_f32_e32 v22, v22, v23
	v_mov_b32_e32 v23, v22
	s_nop 1
	v_permlane32_swap_b32_e32 v22, v23
	v_add_f32_e32 v22, v22, v23
	v_mov_b32_e32 v23, v22
	s_nop 1
	v_permlane16_swap_b32_e32 v22, v23
	v_add_f32_e32 v22, v22, v23
	s_nop 1
	v_add_f32_dpp v22, v22, v22 row_ror:8 row_mask:0xf bank_mask:0xf
	s_nop 1
	v_add_f32_dpp v22, v22, v22 row_ror:4 row_mask:0xf bank_mask:0xf
	s_nop 1
	v_add_f32_dpp v22, v22, v22 quad_perm:[2,3,0,1] row_mask:0xf bank_mask:0xf
	s_nop 1
	v_add_f32_dpp v22, v22, v22 quad_perm:[1,0,3,2] row_mask:0xf bank_mask:0xf
	v_fmamk_f32 v22, v22, 0x3c000000, v170
	v_cmp_gt_f32_e32 vcc, s33, v22
	v_mul_f32_e32 v23, 0x4b800000, v22
	s_nop 0
	v_cndmask_b32_e32 v22, v22, v23, vcc
	v_rsq_f32_e32 v22, v22
	s_nop 0
	v_mul_f32_e32 v23, 0x45800000, v22
	v_cndmask_b32_e32 v22, v22, v23, vcc
	v_pk_mul_f32 v[20:21], v[22:23], v[20:21] op_sel_hi:[0,1]
	v_cvt_pk_bf16_f32 v20, v20, v21
	ds_write_b32 v59, v20 offset:272
	s_waitcnt vmcnt(28)
	v_lshlrev_b32_e32 v20, 16, v53
	v_and_b32_e32 v21, 0xffff0000, v53
	ds_bpermute_b32 v53, v28, v20
	ds_bpermute_b32 v23, v28, v21
	s_waitcnt lgkmcnt(0)
	v_mul_f32_e32 v20, v92, v20
	v_mul_f32_e32 v21, v93, v21
	v_fmac_f32_e32 v20, v94, v53
	v_fmac_f32_e32 v21, v95, v23
	v_cvt_pk_bf16_f32 v22, v20, v21
	v_add_co_u32_e32 v20, vcc, 0xa002000, v18
	s_nop 1
	v_addc_co_u32_e32 v21, vcc, 0, v19, vcc
	global_store_dword v[20:21], v22, off offset:1280
	s_waitcnt vmcnt(28)
	v_lshlrev_b32_e32 v20, 16, v52
	v_and_b32_e32 v21, 0xffff0000, v52
	ds_bpermute_b32 v52, v28, v20
	s_waitcnt lgkmcnt(1)
	ds_bpermute_b32 v23, v28, v21
	s_and_saveexec_b64 s[2:3], s[12:13]
	s_xor_b64 s[18:19], exec, s[2:3]
	s_cbranch_execz .LBB0_254
	s_and_saveexec_b64 s[30:31], s[14:15]
	s_cbranch_execz .LBB0_253
	v_mov_b32_e32 v22, v21
	s_waitcnt lgkmcnt(0)
	v_mul_f32_e32 v20, v212, v20
	v_mul_f32_e32 v21, v214, v22
	v_fmac_f32_e32 v20, v213, v52
	v_fmac_f32_e32 v21, v215, v23

; DI unsigned pk2(float lo, float hi) { f32x2 x = {lo, hi}; return __builtin_bit_cast(unsigned, __builtin_convertvector(x, bf16x2_t)); }
; DI float sum16(float v) { v += __shfl_xor(v, 8); v += __shfl_xor(v, 4); v += __shfl_xor(v, 2); v += __shfl_xor(v, 1); return v; }
; DI void post_unit(const Params& p, int l, int unit, LAS unsigned char* lds) {
;     ...
;       } else {
;         const float* gn = (s < 14) ? qnc : knc;
;         const float rs = rsqrtf(sum16(x[0] * x[0] + x[1] * x[1]) * (1.0f / 32.0f) + EPS);
;         x[0] *= rs * gn[2 * hl16]; x[1] *= rs * gn[2 * hl16 + 1]; rope2<2>(x, hl16, cs8 + t * 4);
;         if (s < 14) x *= LOG2E * 0.17677669529663687f;
;         *(unsigned*)pp = pk2(x[0], x[1]);
.LBB0_296:
	s_or_b64 exec, exec, s[18:19]
	s_mov_b32 s2, 0x3e8293ee
	s_waitcnt lgkmcnt(0)
	v_pk_mul_f32 v[20:21], v[22:23], s[2:3] op_sel_hi:[1,0]
	s_nop 0
	v_cvt_pk_bf16_f32 v22, v20, v21
	v_add_co_u32_e32 v20, vcc, 0xa003000, v18
	s_nop 1
	v_addc_co_u32_e32 v21, vcc, 0, v19, vcc
	global_store_dword v[20:21], v22, off offset:896
	s_waitcnt vmcnt(27)
	v_lshlrev_b32_e32 v20, 16, v42
	v_and_b32_e32 v21, 0xffff0000, v42
	v_pk_mul_f32 v[22:23], v[20:21], v[20:21]
	s_nop 0
	v_add_f32_e32 v22, v22, v23
	s_nop 1
	v_add_f32_dpp v22, v22, v22 row_ror:8 row_mask:0xf bank_mask:0xf
	s_nop 1
	v_add_f32_dpp v22, v22, v22 row_ror:4 row_mask:0xf bank_mask:0xf
	s_nop 1
	v_add_f32_dpp v22, v22, v22 quad_perm:[2,3,0,1] row_mask:0xf bank_mask:0xf
	s_nop 1
	v_add_f32_dpp v22, v22, v22 quad_perm:[1,0,3,2] row_mask:0xf bank_mask:0xf
	v_fmamk_f32 v22, v22, 0x3d000000, v170
	v_cmp_gt_f32_e32 vcc, s33, v22
	v_mul_f32_e32 v23, 0x4b800000, v22
	s_nop 0
	v_cndmask_b32_e32 v22, v22, v23, vcc
	v_rsq_f32_e32 v22, v22
	s_nop 0
	v_mul_f32_e32 v23, 0x45800000, v22
	v_cndmask_b32_e32 v22, v22, v23, vcc
	v_pk_mul_f32 v[22:23], v[6:7], v[22:23] op_sel_hi:[1,0]
	s_nop 0
	v_pk_mul_f32 v[22:23], v[22:23], v[20:21]
	ds_bpermute_b32 v20, v29, v22
	ds_bpermute_b32 v21, v29, v23
	s_waitcnt lgkmcnt(0)
	v_mul_f32_e32 v22, v96, v22
	v_mul_f32_e32 v23, v97, v23
	v_fmac_f32_e32 v22, v98, v20
	v_fmac_f32_e32 v23, v99, v21
	s_mov_b32 s2, 0x3e8293ee
	s_waitcnt lgkmcnt(0)
	v_pk_mul_f32 v[20:21], v[22:23], s[2:3] op_sel_hi:[1,0]
	s_nop 0
	v_cvt_pk_bf16_f32 v22, v20, v21
	v_add_co_u32_e32 v20, vcc, 0xa003000, v18
	s_nop 1
	v_addc_co_u32_e32 v21, vcc, 0, v19, vcc
	global_store_dword v[20:21], v22, off offset:1152
	s_waitcnt vmcnt(27)
	v_lshlrev_b32_e32 v20, 16, v41
	v_and_b32_e32 v21, 0xffff0000, v41
	v_pk_mul_f32 v[22:23], v[20:21], v[20:21]
	s_nop 0
	v_add_f32_e32 v22, v22, v23
	s_nop 1
	v_add_f32_dpp v22, v22, v22 row_ror:8 row_mask:0xf bank_mask:0xf
	s_nop 1
	v_add_f32_dpp v22, v22, v22 row_ror:4 row_mask:0xf bank_mask:0xf
	s_nop 1
	v_add_f32_dpp v22, v22, v22 quad_perm:[2,3,0,1] row_mask:0xf bank_mask:0xf
	s_nop 1
	v_add_f32_dpp v22, v22, v22 quad_perm:[1,0,3,2] row_mask:0xf bank_mask:0xf
	v_fmamk_f32 v22, v22, 0x3d000000, v170
	v_cmp_gt_f32_e32 vcc, s33, v22
	v_mul_f32_e32 v23, 0x4b800000, v22
	s_nop 0
	v_cndmask_b32_e32 v22, v22, v23, vcc
	v_rsq_f32_e32 v22, v22
	s_nop 0
	v_mul_f32_e32 v23, 0x45800000, v22
	v_cndmask_b32_e32 v22, v22, v23, vcc
	v_pk_mul_f32 v[22:23], v[8:9], v[22:23] op_sel_hi:[1,0]
	s_nop 0
	v_pk_mul_f32 v[22:23], v[22:23], v[20:21]
	ds_bpermute_b32 v20, v29, v22
	ds_bpermute_b32 v21, v29, v23
	s_waitcnt lgkmcnt(0)
	v_mul_f32_e32 v22, v96, v22
	v_mul_f32_e32 v23, v97, v23
	v_fmac_f32_e32 v22, v98, v20
	v_fmac_f32_e32 v23, v99, v21
	s_waitcnt lgkmcnt(1)
	v_add_co_u32_e32 v20, vcc, 0xa003000, v18
	v_cvt_pk_bf16_f32 v22, v22, v23
	s_waitcnt lgkmcnt(0)
	v_addc_co_u32_e32 v21, vcc, 0, v19, vcc
	global_store_dword v[20:21], v22, off offset:1408
	s_waitcnt vmcnt(27)
	v_lshlrev_b32_e32 v20, 16, v3
	v_and_b32_e32 v21, 0xffff0000, v3
	v_pk_mul_f32 v[22:23], v[20:21], v[20:21]
	s_nop 0
	v_add_f32_e32 v3, v22, v23
	s_nop 1
	v_add_f32_dpp v3, v3, v3 row_ror:8 row_mask:0xf bank_mask:0xf
	s_nop 1
	v_add_f32_dpp v3, v3, v3 row_ror:4 row_mask:0xf bank_mask:0xf
	s_nop 1
	v_add_f32_dpp v3, v3, v3 quad_perm:[2,3,0,1] row_mask:0xf bank_mask:0xf
	s_nop 1
	v_add_f32_dpp v3, v3, v3 quad_perm:[1,0,3,2] row_mask:0xf bank_mask:0xf
	v_fmamk_f32 v3, v3, 0x3d000000, v170
	v_cmp_gt_f32_e32 vcc, s33, v3
	v_mul_f32_e32 v22, 0x4b800000, v3
	s_nop 0
	v_cndmask_b32_e32 v3, v3, v22, vcc
	v_rsq_f32_e32 v3, v3
	s_nop 0
	v_mul_f32_e32 v22, 0x45800000, v3
	v_cndmask_b32_e32 v22, v3, v22, vcc
	v_pk_mul_f32 v[22:23], v[8:9], v[22:23] op_sel_hi:[1,0]
	s_nop 0
	v_pk_mul_f32 v[22:23], v[22:23], v[20:21]
	ds_bpermute_b32 v3, v29, v22
	ds_bpermute_b32 v21, v29, v23
	s_and_saveexec_b64 s[2:3], s[6:7]
	s_xor_b64 s[18:19], exec, s[2:3]
	s_cbranch_execz .LBB0_312
	s_and_saveexec_b64 s[30:31], s[8:9]
	s_cbranch_execz .LBB0_311
	v_mov_b32_e32 v20, v23
	s_waitcnt lgkmcnt(0)
	v_mul_f32_e32 v22, v22, v228
	v_mul_f32_e32 v23, v20, v230
	v_fmac_f32_e32 v22, v229, v3
	v_fmac_f32_e32 v23, v21, v231
